# mlstmA: conv loads issued before the gate chain on wave 0 (after its gate loads) and at item top on waves 1-7
# baseline (speedup 1.0000x reference)
; DI void conv_unit(const u16* __restrict__ PM, const float* __restrict__ conv_w, const float* __restrict__ conv_b, int b, int sl0, int ch, float scale, float* a8) {
;   { const float4 b0 = *(const float4*)(conv_b + ch), b1 = *(const float4*)(conv_b + ch + 4); a8[0] = b0.x; a8[1] = b0.y; a8[2] = b0.z; a8[3] = b0.w; a8[4] = b1.x; a8[5] = b1.y; a8[6] = b1.z; a8[7] = b1.w; }
; #pragma unroll
;   for (int j = 0; j < 4; ++j) {
;     const int sl = sl0 - 3 + j;
;     if (sl >= 0) {
;       const uint4 raw = *(const uint4*)(PM + ((size_t)b * SEQ + sl) * 1024 + ch);
;       float x8[8]; unpack8(raw, x8);
;       const float4 w0 = *(const float4*)(conv_w + j * 1024 + ch), w1 = *(const float4*)(conv_w + j * 1024 + ch + 4);
;       a8[0] += w0.x * x8[0]; a8[1] += w0.y * x8[1]; a8[2] += w0.z * x8[2]; a8[3] += w0.w * x8[3];
;       a8[4] += w1.x * x8[4]; a8[5] += w1.y * x8[5]; a8[6] += w1.z * x8[6]; a8[7] += w1.w * x8[7];
;     }
;   }
; DI void mlstmA_item(const Params& p, char* lds, int item) {
;     ...
;   if (wave == 0) {
;     const size_t row = (size_t)b * SEQ + c * 64 + lane;
;     const float ig = G[row * 8 + hd] + p.in[7][hd], fg = G[row * 8 + 4 + hd] + p.in[8][hd];
.LBB0_324:
	v_readfirstlane_b32 s72, v222
	s_nop 3
	s_cmp_lt_u32 s72, 64
	s_cbranch_scc1 .Lma_noissue
	v_and_b32_e32 v70, 15, v222
	s_bfe_u32 s72, s10, 0x20007
	v_lshlrev_b32_e32 v70, 3, v70
	s_lshl_b32 s72, s72, 7
	v_add_u32_e32 v70, s72, v70
	v_lshlrev_b32_e32 v71, 2, v70
	v_add_u32_e32 v72, 0x1000, v71
	v_add_u32_e32 v73, 0x2000, v71
	v_add_u32_e32 v74, 0x3000, v71
	global_load_dwordx4 v[140:143], v71, s[62:63] offset:2048
	global_load_dwordx4 v[144:147], v71, s[62:63] offset:2064
	global_load_dwordx4 v[148:151], v72, s[62:63] offset:2048
	global_load_dwordx4 v[152:155], v72, s[62:63] offset:2064
	global_load_dwordx4 v[156:159], v73, s[62:63] offset:2048
	global_load_dwordx4 v[160:163], v73, s[62:63] offset:2064
	global_load_dwordx4 v[164:167], v74, s[62:63] offset:2048
	global_load_dwordx4 v[168:171], v74, s[62:63] offset:2064
	global_load_dwordx4 v[224:227], v71, s[64:65] offset:2048
	global_load_dwordx4 v[228:231], v71, s[64:65] offset:2064
	s_ashr_i32 s74, s10, 9
	s_ashr_i32 s75, s74, 31
	s_lshl_b64 s[74:75], s[74:75], 24
	s_add_u32 s74, s74, s4
	s_addc_u32 s75, s75, s5
	v_lshlrev_b32_e32 v76, 1, v70
	v_mov_b32_e32 v77, 0
	v_lshl_add_u64 v[78:79], s[74:75], 0, v[76:77]
	s_and_b32 s76, s10, 0x7f
	s_lshl_b32 s76, s76, 6
	v_lshrrev_b32_e32 v75, 4, v222
	s_movk_i32 s77, 0x800
	v_add_u32_e32 v184, s76, v75
	v_add_u32_e32 v185, -1, v184
	v_mov_b32_e32 v114, 0
	v_mov_b32_e32 v115, 0
	v_mov_b32_e32 v116, 0
	v_mov_b32_e32 v117, 0
	v_mov_b32_e32 v118, 0
	v_mov_b32_e32 v119, 0
	v_mov_b32_e32 v120, 0
	v_mov_b32_e32 v121, 0
	v_mov_b32_e32 v122, 0
	v_mov_b32_e32 v123, 0
	v_mov_b32_e32 v124, 0
	v_mov_b32_e32 v125, 0
	v_mad_i64_i32 v[186:187], s[88:89], v185, s77, v[78:79]
	v_cmp_lt_i32_e64 s[84:85], 2, v184
	s_and_saveexec_b64 s[86:87], s[84:85]
	global_load_dwordx4 v[114:117], v[186:187], off offset:-3072
	s_or_b64 exec, exec, s[86:87]
	v_cmp_lt_i32_e64 s[84:85], 1, v184
	s_and_saveexec_b64 s[86:87], s[84:85]
	global_load_dwordx4 v[118:121], v[186:187], off offset:-1024
	s_or_b64 exec, exec, s[86:87]
	v_cmp_lt_i32_e64 s[84:85], 0, v184
	s_and_saveexec_b64 s[86:87], s[84:85]
	global_load_dwordx4 v[122:125], v[186:187], off offset:1024
	s_or_b64 exec, exec, s[86:87]
	global_load_dwordx4 v[126:129], v[186:187], off offset:3072
	v_add_u32_e32 v184, 32, v184
	v_add_u32_e32 v185, -1, v184
	v_mov_b32_e32 v130, 0
	v_mov_b32_e32 v131, 0
	v_mov_b32_e32 v132, 0
	v_mov_b32_e32 v133, 0
	v_mov_b32_e32 v134, 0
	v_mov_b32_e32 v135, 0
	v_mov_b32_e32 v136, 0
	v_mov_b32_e32 v137, 0
	v_mov_b32_e32 v172, 0
	v_mov_b32_e32 v173, 0
	v_mov_b32_e32 v174, 0
	v_mov_b32_e32 v175, 0
	v_mad_i64_i32 v[186:187], s[88:89], v185, s77, v[78:79]
	v_cmp_lt_i32_e64 s[84:85], 2, v184
	s_and_saveexec_b64 s[86:87], s[84:85]
	global_load_dwordx4 v[130:133], v[186:187], off offset:-3072
	s_or_b64 exec, exec, s[86:87]
	v_cmp_lt_i32_e64 s[84:85], 1, v184
	s_and_saveexec_b64 s[86:87], s[84:85]
	global_load_dwordx4 v[134:137], v[186:187], off offset:-1024
	s_or_b64 exec, exec, s[86:87]
	v_cmp_lt_i32_e64 s[84:85], 0, v184
	s_and_saveexec_b64 s[86:87], s[84:85]
	global_load_dwordx4 v[172:175], v[186:187], off offset:1024
	s_or_b64 exec, exec, s[86:87]
	global_load_dwordx4 v[176:179], v[186:187], off offset:3072
.Lma_noissue:
	v_mov_b32_e32 v18, v222
	s_and_b32 s18, s10, 0x7f
	s_ashr_i32 s12, s10, 9
	s_nop 0
	v_cmp_lt_u32_e32 vcc, 63, v18
	s_and_saveexec_b64 s[0:1], vcc
	s_xor_b64 s[0:1], exec, s[0:1]
	s_lshl_b32 s8, s18, 6
	s_ashr_i32 s13, s12, 31
	s_or_saveexec_b64 s[14:15], s[0:1]
	s_bfe_u32 s27, s10, 0x20007
	v_and_b32_e32 v19, 63, v18
	s_ashr_i32 s11, s10, 31
	v_mov_b64_e32 v[10:11], s[12:13]
	v_mov_b64_e32 v[0:1], s[8:9]
	v_mov_b32_e32 v50, s8
	s_xor_b64 exec, exec, s[14:15]
	s_cbranch_execz .LBB0_330
	s_ashr_i32 s13, s12, 31
	s_lshl_b64 s[0:1], s[12:13], 13
	s_lshl_b32 s18, s18, 6
	v_or_b32_e32 v0, s0, v18
	v_or_b32_e32 v0, s18, v0
	v_mov_b32_e32 v1, s1
	v_lshlrev_b64 v[0:1], 5, v[0:1]
	v_lshl_add_u64 v[0:1], s[52:53], 0, v[0:1]
	s_lshl_b32 s8, s27, 2
	v_lshl_add_u64 v[2:3], v[0:1], 0, s[8:9]
	v_mov_b32_e32 v1, s8
	global_load_dword v0, v[2:3], off
	global_load_dword v4, v1, s[66:67]
	s_nop 0
	global_load_dword v2, v[2:3], off offset:16
	s_nop 0
	global_load_dword v1, v1, s[36:37]
	v_and_b32_e32 v70, 15, v222
	s_bfe_u32 s72, s10, 0x20007
	v_lshlrev_b32_e32 v70, 3, v70
	s_lshl_b32 s72, s72, 7
	v_add_u32_e32 v70, s72, v70
	v_lshlrev_b32_e32 v71, 2, v70
	v_add_u32_e32 v72, 0x1000, v71
	v_add_u32_e32 v73, 0x2000, v71
	v_add_u32_e32 v74, 0x3000, v71
	global_load_dwordx4 v[140:143], v71, s[62:63] offset:2048
	global_load_dwordx4 v[144:147], v71, s[62:63] offset:2064
	global_load_dwordx4 v[148:151], v72, s[62:63] offset:2048
	global_load_dwordx4 v[152:155], v72, s[62:63] offset:2064
	global_load_dwordx4 v[156:159], v73, s[62:63] offset:2048
	global_load_dwordx4 v[160:163], v73, s[62:63] offset:2064
	global_load_dwordx4 v[164:167], v74, s[62:63] offset:2048
	global_load_dwordx4 v[168:171], v74, s[62:63] offset:2064
	global_load_dwordx4 v[224:227], v71, s[64:65] offset:2048
	global_load_dwordx4 v[228:231], v71, s[64:65] offset:2064
	s_ashr_i32 s74, s10, 9
	s_ashr_i32 s75, s74, 31
	s_lshl_b64 s[74:75], s[74:75], 24
	s_add_u32 s74, s74, s4
	s_addc_u32 s75, s75, s5
	v_lshlrev_b32_e32 v76, 1, v70
	v_mov_b32_e32 v77, 0
	v_lshl_add_u64 v[78:79], s[74:75], 0, v[76:77]
	s_and_b32 s76, s10, 0x7f
	s_lshl_b32 s76, s76, 6
	v_lshrrev_b32_e32 v75, 4, v222
	s_movk_i32 s77, 0x800
	v_add_u32_e32 v184, s76, v75
	v_add_u32_e32 v185, -1, v184
	v_mov_b32_e32 v114, 0
	v_mov_b32_e32 v115, 0
	v_mov_b32_e32 v116, 0
	v_mov_b32_e32 v117, 0
	v_mov_b32_e32 v118, 0
	v_mov_b32_e32 v119, 0
	v_mov_b32_e32 v120, 0
	v_mov_b32_e32 v121, 0
; DI float scan_sum(float v, int lane) { for (int o = 1; o < 64; o <<= 1) { float tv = __shfl_up(v, o); if (lane >= o) v += tv; } return v; }
; DI float log_sigmoid(float f) { return fminf(f, 0.f) - log1pf(expf(-fabsf(f))); }
; DI void mlstmA_item(const Params& p, char* lds, int item) {
;     ...
;   if (wave == 0) {
;     const size_t row = (size_t)b * SEQ + c * 64 + lane;
;     const float ig = G[row * 8 + hd] + p.in[7][hd], fg = G[row * 8 + 4 + hd] + p.in[8][hd];
;     const float bc = scan_sum(log_sigmoid(fg), lane);
	v_mov_b32_e32 v122, 0
	v_mov_b32_e32 v123, 0
	v_mov_b32_e32 v124, 0
	v_mov_b32_e32 v125, 0
	v_mad_i64_i32 v[186:187], s[88:89], v185, s77, v[78:79]
	v_cmp_lt_i32_e64 s[84:85], 2, v184
	s_and_saveexec_b64 s[86:87], s[84:85]
	global_load_dwordx4 v[114:117], v[186:187], off offset:-3072
	s_or_b64 exec, exec, s[86:87]
	v_cmp_lt_i32_e64 s[84:85], 1, v184
	s_and_saveexec_b64 s[86:87], s[84:85]
	global_load_dwordx4 v[118:121], v[186:187], off offset:-1024
	s_or_b64 exec, exec, s[86:87]
	v_cmp_lt_i32_e64 s[84:85], 0, v184
	s_and_saveexec_b64 s[86:87], s[84:85]
	global_load_dwordx4 v[122:125], v[186:187], off offset:1024
	s_or_b64 exec, exec, s[86:87]
	global_load_dwordx4 v[126:129], v[186:187], off offset:3072
	v_add_u32_e32 v184, 32, v184
	v_add_u32_e32 v185, -1, v184
	v_mov_b32_e32 v130, 0
	v_mov_b32_e32 v131, 0
	v_mov_b32_e32 v132, 0
	v_mov_b32_e32 v133, 0
	v_mov_b32_e32 v134, 0
	v_mov_b32_e32 v135, 0
	v_mov_b32_e32 v136, 0
	v_mov_b32_e32 v137, 0
	v_mov_b32_e32 v172, 0
	v_mov_b32_e32 v173, 0
	v_mov_b32_e32 v174, 0
	v_mov_b32_e32 v175, 0
	v_mad_i64_i32 v[186:187], s[88:89], v185, s77, v[78:79]
	v_cmp_lt_i32_e64 s[84:85], 2, v184
	s_and_saveexec_b64 s[86:87], s[84:85]
	global_load_dwordx4 v[130:133], v[186:187], off offset:-3072
	s_or_b64 exec, exec, s[86:87]
	v_cmp_lt_i32_e64 s[84:85], 1, v184
	s_and_saveexec_b64 s[86:87], s[84:85]
	global_load_dwordx4 v[134:137], v[186:187], off offset:-1024
	s_or_b64 exec, exec, s[86:87]
	v_cmp_lt_i32_e64 s[84:85], 0, v184
	s_and_saveexec_b64 s[86:87], s[84:85]
	global_load_dwordx4 v[172:175], v[186:187], off offset:1024
	s_or_b64 exec, exec, s[86:87]
	global_load_dwordx4 v[176:179], v[186:187], off offset:3072
	s_mov_b32 s0, 0xb2a5705f
	s_waitcnt vmcnt(20)
	v_add_f32_e32 v0, v0, v4
	s_waitcnt vmcnt(18)
	v_add_f32_e32 v1, v2, v1
	v_mul_f32_e64 v2, |v1|, s23
	v_fma_f32 v3, |v1|, s23, -v2
	v_rndne_f32_e32 v5, v2
	v_fma_f32 v3, |v1|, s0, v3
	v_sub_f32_e32 v2, v2, v5
	v_add_f32_e32 v2, v2, v3
	v_exp_f32_e32 v2, v2
	v_cvt_i32_f32_e32 v3, v5
	s_mov_b32 s0, 0x42ce8ed0
	v_cmp_ngt_f32_e64 vcc, |v1|, s0
	s_mov_b32 s0, 0xc2b17218
	v_ldexp_f32 v2, v2, v3
	v_cndmask_b32_e32 v2, 0, v2, vcc
	v_cmp_nlt_f32_e64 vcc, |v1|, s0
	v_min_f32_e32 v4, 0, v1
	s_mov_b32 s0, 0x3f2aaaab
	v_cndmask_b32_e32 v1, v33, v2, vcc
	v_add_f32_e32 v5, 1.0, v1
	v_add_f32_e32 v2, -1.0, v5
	v_sub_f32_e32 v3, v2, v5
	v_add_f32_e32 v3, 1.0, v3
	v_sub_f32_e32 v2, v1, v2
	v_add_f32_e32 v6, v2, v3
	v_frexp_mant_f32_e32 v2, v5
	v_cmp_gt_f32_e32 vcc, s0, v2
	v_cvt_f64_f32_e32 v[2:3], v5
	v_frexp_exp_i32_f64_e32 v2, v[2:3]
	v_subbrev_co_u32_e32 v2, vcc, 0, v2, vcc
	v_sub_u32_e32 v3, 0, v2
	v_ldexp_f32 v5, v5, v3
	v_ldexp_f32 v3, v6, v3
	v_add_f32_e32 v6, -1.0, v5
	v_add_f32_e32 v7, 1.0, v6
	v_sub_f32_e32 v7, v5, v7
	v_add_f32_e32 v7, v3, v7
	v_add_f32_e32 v8, v6, v7
	v_sub_f32_e32 v6, v6, v8
	v_add_f32_e32 v6, v7, v6
	v_add_f32_e32 v7, 1.0, v5
	v_add_f32_e32 v9, -1.0, v7
	v_sub_f32_e32 v5, v5, v9
	v_add_f32_e32 v3, v3, v5
	v_add_f32_e32 v5, v7, v3
	v_sub_f32_e32 v7, v7, v5
	v_add_f32_e32 v3, v3, v7
	v_rcp_f32_e32 v7, v5
	v_cvt_f32_i32_e32 v2, v2
	s_mov_b32 s0, 0x3f317218
	v_mul_f32_e32 v9, v8, v7
	v_mul_f32_e32 v10, v5, v9
	v_fma_f32 v11, v9, v5, -v10
	v_fmac_f32_e32 v11, v9, v3
	v_add_f32_e32 v12, v10, v11
	v_sub_f32_e32 v13, v8, v12
	v_sub_f32_e32 v8, v8, v13
	v_sub_f32_e32 v10, v12, v10
	v_sub_f32_e32 v8, v8, v12
	v_add_f32_e32 v6, v6, v8
	v_sub_f32_e32 v8, v10, v11
	v_add_f32_e32 v6, v8, v6
	v_add_f32_e32 v8, v13, v6
	v_mul_f32_e32 v10, v7, v8
	v_mul_f32_e32 v11, v5, v10
	v_fma_f32 v5, v10, v5, -v11
	v_fmac_f32_e32 v5, v10, v3
	v_sub_f32_e32 v3, v13, v8
	v_add_f32_e32 v3, v6, v3
	v_add_f32_e32 v6, v11, v5
	v_sub_f32_e32 v12, v8, v6
	v_sub_f32_e32 v8, v8, v12
	v_sub_f32_e32 v11, v6, v11
	v_sub_f32_e32 v6, v8, v6
	v_add_f32_e32 v3, v3, v6
	v_sub_f32_e32 v5, v11, v5
	v_add_f32_e32 v3, v5, v3
	v_add_f32_e32 v5, v9, v10
	v_add_f32_e32 v3, v12, v3
	v_sub_f32_e32 v6, v5, v9
	v_mul_f32_e32 v3, v7, v3
	v_sub_f32_e32 v6, v10, v6
	v_add_f32_e32 v3, v6, v3
	v_mul_f32_e32 v9, 0x3f317218, v2
	v_add_f32_e32 v6, v5, v3
	v_fma_f32 v10, v2, s0, -v9
	v_mul_f32_e32 v7, v6, v6
	v_fmac_f32_e32 v10, 0xb102e308, v2
	v_sub_f32_e32 v2, v6, v5
	v_fmamk_f32 v8, v7, 0x3e9b6dac, v32
	v_sub_f32_e32 v2, v3, v2
	v_add_f32_e32 v3, v9, v10
	v_fmaak_f32 v8, v7, v8, 0x3f2aaada
	v_sub_f32_e32 v5, v3, v9
	v_ldexp_f32 v9, v6, 1
	v_mul_f32_e32 v6, v6, v7
	v_mul_f32_e32 v6, v6, v8
	v_add_f32_e32 v7, v9, v6
	v_sub_f32_e32 v8, v7, v9
	v_ldexp_f32 v2, v2, 1
	v_sub_f32_e32 v6, v6, v8
	v_add_f32_e32 v2, v2, v6
	v_add_f32_e32 v6, v7, v2
	v_sub_f32_e32 v7, v6, v7
	v_sub_f32_e32 v2, v2, v7
	v_add_f32_e32 v7, v3, v6
	v_sub_f32_e32 v8, v7, v3
	v_sub_f32_e32 v9, v7, v8
	v_sub_f32_e32 v5, v10, v5
	v_sub_f32_e32 v3, v3, v9
	v_sub_f32_e32 v6, v6, v8
	v_add_f32_e32 v3, v6, v3
	v_add_f32_e32 v6, v5, v2
	v_sub_f32_e32 v8, v6, v5
	v_sub_f32_e32 v9, v6, v8
	v_sub_f32_e32 v5, v5, v9
	v_sub_f32_e32 v2, v2, v8
	v_add_f32_e32 v3, v6, v3
	v_add_f32_e32 v2, v2, v5
	v_add_f32_e32 v5, v7, v3
	v_sub_f32_e32 v6, v5, v7
	v_sub_f32_e32 v3, v3, v6
	v_add_f32_e32 v2, v2, v3
	s_mov_b32 s0, 0x7f800000
	v_add_f32_e32 v2, v5, v2
	v_cmp_neq_f32_e32 vcc, s0, v1
	s_mov_b32 s0, 0x33800000
	s_nop 0
	v_cndmask_b32_e32 v2, v33, v2, vcc
	v_cmp_lt_f32_e64 vcc, |v1|, s0
	v_cmp_lt_i32_e64 s[0:1], v37, v35
	s_nop 0
	v_cndmask_b32_e32 v1, v2, v1, vcc
	v_cmp_lt_i32_e32 vcc, v36, v35
	v_sub_f32_e32 v1, v4, v1
	s_nop 0
	v_cndmask_b32_e32 v2, v36, v34, vcc
	v_lshlrev_b32_e32 v2, 2, v2
	ds_bpermute_b32 v2, v2, v1
	v_cmp_eq_u32_e32 vcc, 0, v19
	s_waitcnt lgkmcnt(0)
; DI float wmax(float v) { for (int o = 32; o; o >>= 1) v = fmaxf(v, __shfl_xor(v, o)); return v; }
; DI float log_sigmoid(float f) { return fminf(f, 0.f) - log1pf(expf(-fabsf(f))); }
; DI float scan_sum(float v, int lane) { for (int o = 1; o < 64; o <<= 1) { float tv = __shfl_up(v, o); if (lane >= o) v += tv; } return v; }
; DI void mlstmA_item(const Params& p, char* lds, int item) {
;     ...
;     const float bc = scan_sum(log_sigmoid(fg), lane);
;     const float as = ig - bc;
;     const float gmax = wmax(as);
;     const float B = __shfl(bc, 63);
;     win[lane] = expf(as - gmax);
;     if (lane == 0) { CSC[0] = B; CSC[1] = B + gmax; }
	v_add_f32_e32 v2, v1, v2
	v_cndmask_b32_e32 v1, v2, v1, vcc
	v_cndmask_b32_e64 v2, v37, v34, s[0:1]
	v_lshlrev_b32_e32 v2, 2, v2
	ds_bpermute_b32 v2, v2, v1
	v_cmp_gt_u32_e64 s[0:1], 2, v19
	s_waitcnt lgkmcnt(0)
	v_add_f32_e32 v2, v1, v2
	v_cndmask_b32_e64 v1, v2, v1, s[0:1]
	v_cmp_lt_i32_e64 s[0:1], v38, v35
	s_nop 1
	v_cndmask_b32_e64 v2, v38, v34, s[0:1]
	v_lshlrev_b32_e32 v2, 2, v2
	ds_bpermute_b32 v2, v2, v1
	v_cmp_gt_u32_e64 s[0:1], 4, v19
	s_waitcnt lgkmcnt(0)
	v_add_f32_e32 v2, v1, v2
	v_cndmask_b32_e64 v1, v2, v1, s[0:1]
	v_cmp_lt_i32_e64 s[0:1], v39, v35
	s_nop 1
	v_cndmask_b32_e64 v2, v39, v34, s[0:1]
	v_lshlrev_b32_e32 v2, 2, v2
	ds_bpermute_b32 v2, v2, v1
	v_cmp_gt_u32_e64 s[0:1], 8, v19
	s_waitcnt lgkmcnt(0)
	v_add_f32_e32 v2, v1, v2
	v_cndmask_b32_e64 v1, v2, v1, s[0:1]
	v_cmp_lt_i32_e64 s[0:1], v40, v35
	s_nop 1
	v_cndmask_b32_e64 v2, v40, v34, s[0:1]
	v_lshlrev_b32_e32 v2, 2, v2
	ds_bpermute_b32 v2, v2, v1
	v_cmp_gt_u32_e64 s[0:1], 16, v19
	s_waitcnt lgkmcnt(0)
	v_add_f32_e32 v2, v1, v2
	v_cndmask_b32_e64 v1, v2, v1, s[0:1]
	v_cmp_lt_i32_e64 s[0:1], v41, v35
	s_nop 1
	v_cndmask_b32_e64 v2, v41, v34, s[0:1]
	v_lshlrev_b32_e32 v2, 2, v2
	ds_bpermute_b32 v2, v2, v1
	v_cmp_gt_u32_e64 s[0:1], 32, v19
	s_waitcnt lgkmcnt(0)
	v_add_f32_e32 v2, v1, v2
	v_cndmask_b32_e64 v2, v2, v1, s[0:1]
	v_cmp_lt_i32_e64 s[0:1], v43, v42
	v_sub_f32_e32 v3, v0, v2
	s_nop 0
	v_cndmask_b32_e64 v0, v34, v43, s[0:1]
	v_lshlrev_b32_e32 v0, 2, v0
	ds_bpermute_b32 v0, v0, v3
	v_cmp_lt_i32_e64 s[0:1], v44, v42
	s_waitcnt lgkmcnt(0)
	v_max_f32_e32 v0, v0, v0
	v_cndmask_b32_e64 v1, v34, v44, s[0:1]
	v_max_f32_e32 v0, v3, v0
	v_lshlrev_b32_e32 v1, 2, v1
	ds_bpermute_b32 v1, v1, v0
	v_cmp_lt_i32_e64 s[0:1], v45, v42
	s_waitcnt lgkmcnt(0)
	v_max_f32_e32 v1, v1, v1
	v_max_f32_e32 v0, v0, v1
	v_cndmask_b32_e64 v1, v34, v45, s[0:1]
	v_lshlrev_b32_e32 v1, 2, v1
	ds_bpermute_b32 v1, v1, v0
	v_cmp_lt_i32_e64 s[0:1], v46, v42
	s_waitcnt lgkmcnt(0)
	v_max_f32_e32 v1, v1, v1
	v_max_f32_e32 v0, v0, v1
	v_cndmask_b32_e64 v1, v34, v46, s[0:1]
	v_lshlrev_b32_e32 v1, 2, v1
	ds_bpermute_b32 v1, v1, v0
	v_cmp_lt_i32_e64 s[0:1], v47, v42
	s_waitcnt lgkmcnt(0)
	v_max_f32_e32 v1, v1, v1
	v_max_f32_e32 v0, v0, v1
	v_cndmask_b32_e64 v1, v34, v47, s[0:1]
	v_lshlrev_b32_e32 v1, 2, v1
	ds_bpermute_b32 v1, v1, v0
	v_cmp_lt_i32_e64 s[0:1], v48, v42
	s_waitcnt lgkmcnt(0)
	v_max_f32_e32 v1, v1, v1
	v_max_f32_e32 v0, v0, v1
	v_cndmask_b32_e64 v1, v34, v48, s[0:1]
	v_lshlrev_b32_e32 v1, 2, v1
	ds_bpermute_b32 v1, v1, v0
	s_mov_b32 s0, 0x3fb8aa3b
	s_waitcnt lgkmcnt(0)
	v_max_f32_e32 v1, v1, v1
	v_max_f32_e32 v1, v0, v1
	ds_bpermute_b32 v0, v49, v2
	v_sub_f32_e32 v2, v3, v1
	v_mul_f32_e32 v3, 0x3fb8aa3b, v2
	v_fma_f32 v4, v2, s0, -v3
	v_rndne_f32_e32 v5, v3
	v_fmac_f32_e32 v4, 0x32a5705f, v2
	v_sub_f32_e32 v3, v3, v5
	v_add_f32_e32 v3, v3, v4
	v_exp_f32_e32 v3, v3
	v_cvt_i32_f32_e32 v4, v5
	s_mov_b32 s0, 0xc2ce8ed0
	v_cmp_ngt_f32_e64 s[0:1], s0, v2
	v_ldexp_f32 v3, v3, v4
	s_nop 0
	v_cndmask_b32_e64 v3, 0, v3, s[0:1]
	s_mov_b32 s0, 0x42b17218
	v_cmp_nlt_f32_e64 s[0:1], s0, v2
	s_nop 1
	v_cndmask_b32_e64 v2, v33, v3, s[0:1]
	v_lshl_add_u32 v3, v19, 2, 0
	ds_write_b32 v3, v2 offset:36864
	s_and_saveexec_b64 s[0:1], vcc
	s_cbranch_execz .LBB0_329
	s_lshl_b64 s[30:31], s[10:11], 4
	s_add_u32 s30, s21, s30
	s_addc_u32 s31, s22, s31
	s_waitcnt lgkmcnt(1)
	v_add_f32_e32 v1, v1, v0
	global_store_dwordx2 v17, v[0:1], s[30:31]

; DI u16 f2bf(float x) { return (u16)(pack2(x, 0.f) & 0xffffu); }
; DI void mlstmA_item(const Params& p, char* lds, int item) {
;     ...
;   for (int i = 0; i < 2; ++i) {
;     const int q = tid + 512 * i, e = q >> 3, s8 = (q & 7) * 8;
;     *(uint4*)(VTs + e * 72 + s8) = *(const uint4*)(VTm + ((size_t)(bh * 128 + e)) * SEQ + c * 64 + s8);
;   }
;   __syncthreads();
; #pragma unroll 1
;   for (int i = 0; i < 2; ++i) {
;     const int cgk = tid & 15, t = (tid >> 4) + 32 * i;
;     float a8[8];
;     conv_unit(PM, p.in[5], p.in[6], b, c * 64 + t, 512 + hd * 128 + cgk * 8, 0.08838834764831845f, a8);
;     const float w = win[t];
; #pragma unroll
;     for (int e = 0; e < 8; ++e) KTs[(cgk * 8 + e) * 72 + t] = f2bf(a8[e] * w);
.LBB0_330:
	s_or_b64 exec, exec, s[14:15]
	v_add_u32_e32 v4, 0x200, v18
	s_and_b32 s0, s10, 0xffffff80
	v_lshlrev_b32_e32 v2, 4, v18
	v_ashrrev_i32_e32 v9, 3, v18
	v_ashrrev_i32_e32 v14, 3, v4
	v_and_b32_e32 v16, 0x70, v2
	v_add_u32_e32 v2, s0, v9
	v_add_u32_e32 v4, s0, v14
	v_lshl_add_u64 v[0:1], v[0:1], 1, s[6:7]
	v_ashrrev_i32_e32 v3, 31, v2
	v_ashrrev_i32_e32 v5, 31, v4
	v_lshl_add_u64 v[0:1], v[0:1], 0, v[16:17]
	v_lshlrev_b64 v[2:3], 14, v[2:3]
	v_lshlrev_b64 v[4:5], 14, v[4:5]
	v_lshl_add_u64 v[2:3], v[0:1], 0, v[2:3]
	v_lshl_add_u64 v[4:5], v[0:1], 0, v[4:5]
	global_load_dwordx4 v[0:3], v[2:3], off
	s_nop 0
	global_load_dwordx4 v[4:7], v[4:5], off
	v_lshlrev_b32_e32 v8, 3, v18
	v_and_b32_e32 v22, 0x78, v8
	v_add_u32_e32 v8, 0, v16
	v_lshl_or_b32 v15, s27, 7, v22
	v_mad_u64_u32 v[12:13], s[0:1], v9, s26, v[8:9]
	v_lshlrev_b32_e32 v16, 2, v15
	v_mad_u64_u32 v[8:9], s[0:1], v14, s26, v[8:9]
	v_lshlrev_b64 v[10:11], 24, v[10:11]
	v_lshl_add_u64 v[10:11], s[4:5], 0, v[10:11]
	v_mov_b32_e32 v13, v17
	s_mov_b64 s[0:1], 0x1800
	v_ashrrev_i32_e32 v51, 4, v18
	v_mad_u32_u24 v52, v22, s26, 0
	s_mov_b32 s8, 0
	s_waitcnt vmcnt(1)
	ds_write_b128 v12, v[0:3] offset:18432
	s_waitcnt vmcnt(0)
	ds_write_b128 v8, v[4:7] offset:18432
	s_waitcnt lgkmcnt(0)
	s_barrier
	s_waitcnt vmcnt(0)
	v_mov_b32_e32 v197, v51
	v_lshlrev_b32_e32 v196, 2, v197
	ds_read_b32 v196, v196 offset:36864
	v_lshl_add_u32 v198, v197, 1, v52
	v_lshlrev_b32_e32 v188, 16, v114
	v_and_b32_e32 v189, 0xffff0000, v114
	v_lshlrev_b32_e32 v190, 16, v115
	v_and_b32_e32 v191, 0xffff0000, v115
	v_lshlrev_b32_e32 v192, 16, v116
	v_and_b32_e32 v193, 0xffff0000, v116
	v_lshlrev_b32_e32 v194, 16, v117
	v_and_b32_e32 v195, 0xffff0000, v117
	v_pk_fma_f32 v[204:205], v[140:141], v[188:189], v[224:225]
	v_pk_fma_f32 v[206:207], v[142:143], v[190:191], v[226:227]
	v_pk_fma_f32 v[208:209], v[144:145], v[192:193], v[228:229]
	v_pk_fma_f32 v[210:211], v[146:147], v[194:195], v[230:231]
	v_lshlrev_b32_e32 v188, 16, v118
	v_and_b32_e32 v189, 0xffff0000, v118
	v_lshlrev_b32_e32 v190, 16, v119
	v_and_b32_e32 v191, 0xffff0000, v119
	v_lshlrev_b32_e32 v192, 16, v120
	v_and_b32_e32 v193, 0xffff0000, v120
	v_lshlrev_b32_e32 v194, 16, v121
	v_and_b32_e32 v195, 0xffff0000, v121
	v_pk_fma_f32 v[204:205], v[148:149], v[188:189], v[204:205]
	v_pk_fma_f32 v[206:207], v[150:151], v[190:191], v[206:207]
	v_pk_fma_f32 v[208:209], v[152:153], v[192:193], v[208:209]
	v_pk_fma_f32 v[210:211], v[154:155], v[194:195], v[210:211]
	v_lshlrev_b32_e32 v188, 16, v122
	v_and_b32_e32 v189, 0xffff0000, v122
	v_lshlrev_b32_e32 v190, 16, v123
	v_and_b32_e32 v191, 0xffff0000, v123
	v_lshlrev_b32_e32 v192, 16, v124
	v_and_b32_e32 v193, 0xffff0000, v124
	v_lshlrev_b32_e32 v194, 16, v125
	v_and_b32_e32 v195, 0xffff0000, v125
	v_pk_fma_f32 v[204:205], v[156:157], v[188:189], v[204:205]
	v_pk_fma_f32 v[206:207], v[158:159], v[190:191], v[206:207]
	v_pk_fma_f32 v[208:209], v[160:161], v[192:193], v[208:209]
	v_pk_fma_f32 v[210:211], v[162:163], v[194:195], v[210:211]
	v_lshlrev_b32_e32 v188, 16, v126
	v_and_b32_e32 v189, 0xffff0000, v126
	v_lshlrev_b32_e32 v190, 16, v127
	v_and_b32_e32 v191, 0xffff0000, v127
	v_lshlrev_b32_e32 v192, 16, v128
	v_and_b32_e32 v193, 0xffff0000, v128
	v_lshlrev_b32_e32 v194, 16, v129
	v_and_b32_e32 v195, 0xffff0000, v129
	v_pk_fma_f32 v[204:205], v[164:165], v[188:189], v[204:205]
	v_pk_fma_f32 v[206:207], v[166:167], v[190:191], v[206:207]
	v_pk_fma_f32 v[208:209], v[168:169], v[192:193], v[208:209]
	v_pk_fma_f32 v[210:211], v[170:171], v[194:195], v[210:211]
	v_mul_f32_e32 v212, 0xbfb8aa3b, v204
	v_mul_f32_e32 v213, 0xbfb8aa3b, v205
	v_mul_f32_e32 v214, 0xbfb8aa3b, v206
	v_mul_f32_e32 v215, 0xbfb8aa3b, v207
	v_mul_f32_e32 v216, 0xbfb8aa3b, v208
	v_mul_f32_e32 v217, 0xbfb8aa3b, v209
	v_mul_f32_e32 v218, 0xbfb8aa3b, v210
	v_mul_f32_e32 v219, 0xbfb8aa3b, v211
	v_mul_f32_e32 v188, 0x3db504f3, v204
	v_mul_f32_e32 v189, 0x3db504f3, v205
	v_mul_f32_e32 v190, 0x3db504f3, v206
	v_mul_f32_e32 v191, 0x3db504f3, v207
	v_mul_f32_e32 v192, 0x3db504f3, v208
	v_mul_f32_e32 v193, 0x3db504f3, v209
	v_mul_f32_e32 v194, 0x3db504f3, v210
	v_mul_f32_e32 v195, 0x3db504f3, v211
	v_exp_f32_e32 v212, v212
	v_exp_f32_e32 v213, v213
	v_exp_f32_e32 v214, v214
	v_exp_f32_e32 v215, v215
	v_exp_f32_e32 v216, v216
	v_exp_f32_e32 v217, v217
	v_exp_f32_e32 v218, v218
	v_exp_f32_e32 v219, v219
	v_add_f32_e32 v212, 1.0, v212
	v_add_f32_e32 v213, 1.0, v213
	v_add_f32_e32 v214, 1.0, v214
	v_add_f32_e32 v215, 1.0, v215
	v_add_f32_e32 v216, 1.0, v216
	v_add_f32_e32 v217, 1.0, v217
	v_add_f32_e32 v218, 1.0, v218
	v_add_f32_e32 v219, 1.0, v219
	v_rcp_f32_e32 v212, v212
	v_rcp_f32_e32 v213, v213
	v_rcp_f32_e32 v214, v214
	v_rcp_f32_e32 v215, v215
	v_rcp_f32_e32 v216, v216
	v_rcp_f32_e32 v217, v217
	v_rcp_f32_e32 v218, v218
	v_rcp_f32_e32 v219, v219
	v_mul_f32_e32 v188, v188, v212
	v_mul_f32_e32 v189, v189, v213
	v_mul_f32_e32 v190, v190, v214
	v_mul_f32_e32 v191, v191, v215
	v_mul_f32_e32 v192, v192, v216
	v_mul_f32_e32 v193, v193, v217
	v_mul_f32_e32 v194, v194, v218
	v_mul_f32_e32 v195, v195, v219
	s_waitcnt lgkmcnt(0)
; DI u16 f2bf(float x) { return (u16)(pack2(x, 0.f) & 0xffffu); }
; DI void conv_unit(const u16* __restrict__ PM, const float* __restrict__ conv_w, const float* __restrict__ conv_b, int b, int sl0, int ch, float scale, float* a8) {
;   { const float4 b0 = *(const float4*)(conv_b + ch), b1 = *(const float4*)(conv_b + ch + 4); a8[0] = b0.x; a8[1] = b0.y; a8[2] = b0.z; a8[3] = b0.w; a8[4] = b1.x; a8[5] = b1.y; a8[6] = b1.z; a8[7] = b1.w; }
; #pragma unroll
;   for (int j = 0; j < 4; ++j) {
;     const int sl = sl0 - 3 + j;
;     if (sl >= 0) {
;       const uint4 raw = *(const uint4*)(PM + ((size_t)b * SEQ + sl) * 1024 + ch);
;       float x8[8]; unpack8(raw, x8);
;       const float4 w0 = *(const float4*)(conv_w + j * 1024 + ch), w1 = *(const float4*)(conv_w + j * 1024 + ch + 4);
;       a8[0] += w0.x * x8[0]; a8[1] += w0.y * x8[1]; a8[2] += w0.z * x8[2]; a8[3] += w0.w * x8[3];
;       a8[4] += w1.x * x8[4]; a8[5] += w1.y * x8[5]; a8[6] += w1.z * x8[6]; a8[7] += w1.w * x8[7];
;     }
;   }
; #pragma unroll
;   for (int e = 0; e < 8; ++e) { const float v = a8[e]; a8[e] = scale * v * __builtin_amdgcn_rcpf(1.f + __expf(-v)); }
; }
; DI void mlstmA_item(const Params& p, char* lds, int item) {
;     ...
;     const int cgk = tid & 15, t = (tid >> 4) + 32 * i;
;     float a8[8];
;     conv_unit(PM, p.in[5], p.in[6], b, c * 64 + t, 512 + hd * 128 + cgk * 8, 0.08838834764831845f, a8);
;     const float w = win[t];
; #pragma unroll
;     for (int e = 0; e < 8; ++e) KTs[(cgk * 8 + e) * 72 + t] = f2bf(a8[e] * w);
	v_mul_f32_e32 v188, v196, v188
	v_mul_f32_e32 v189, v196, v189
	v_mul_f32_e32 v190, v196, v190
	v_mul_f32_e32 v191, v196, v191
	v_mul_f32_e32 v192, v196, v192
	v_mul_f32_e32 v193, v196, v193
	v_mul_f32_e32 v194, v196, v194
	v_mul_f32_e32 v195, v196, v195
	v_cvt_pk_bf16_f32 v188, v188, s77
	v_cvt_pk_bf16_f32 v189, v189, s77
	v_cvt_pk_bf16_f32 v190, v190, s77
	v_cvt_pk_bf16_f32 v191, v191, s77
	v_cvt_pk_bf16_f32 v192, v192, s77
	v_cvt_pk_bf16_f32 v193, v193, s77
	v_cvt_pk_bf16_f32 v194, v194, s77
	v_cvt_pk_bf16_f32 v195, v195, s77
	ds_write_b16 v198, v188
	ds_write_b16 v198, v189 offset:144
	ds_write_b16 v198, v190 offset:288
	ds_write_b16 v198, v191 offset:432
	ds_write_b16 v198, v192 offset:576
	ds_write_b16 v198, v193 offset:720
	ds_write_b16 v198, v194 offset:864
	ds_write_b16 v198, v195 offset:1008
	v_add_u32_e32 v197, 32, v51
	v_lshlrev_b32_e32 v196, 2, v197
	ds_read_b32 v196, v196 offset:36864
	v_lshl_add_u32 v198, v197, 1, v52
	v_lshlrev_b32_e32 v188, 16, v130
	v_and_b32_e32 v189, 0xffff0000, v130
	v_lshlrev_b32_e32 v190, 16, v131
	v_and_b32_e32 v191, 0xffff0000, v131
	v_lshlrev_b32_e32 v192, 16, v132
	v_and_b32_e32 v193, 0xffff0000, v132
	v_lshlrev_b32_e32 v194, 16, v133
	v_and_b32_e32 v195, 0xffff0000, v133
	v_pk_fma_f32 v[204:205], v[140:141], v[188:189], v[224:225]
	v_pk_fma_f32 v[206:207], v[142:143], v[190:191], v[226:227]
	v_pk_fma_f32 v[208:209], v[144:145], v[192:193], v[228:229]
	v_pk_fma_f32 v[210:211], v[146:147], v[194:195], v[230:231]
	v_lshlrev_b32_e32 v188, 16, v134
	v_and_b32_e32 v189, 0xffff0000, v134
	v_lshlrev_b32_e32 v190, 16, v135
	v_and_b32_e32 v191, 0xffff0000, v135
	v_lshlrev_b32_e32 v192, 16, v136
	v_and_b32_e32 v193, 0xffff0000, v136
	v_lshlrev_b32_e32 v194, 16, v137
	v_and_b32_e32 v195, 0xffff0000, v137
	v_pk_fma_f32 v[204:205], v[148:149], v[188:189], v[204:205]
	v_pk_fma_f32 v[206:207], v[150:151], v[190:191], v[206:207]
	v_pk_fma_f32 v[208:209], v[152:153], v[192:193], v[208:209]
	v_pk_fma_f32 v[210:211], v[154:155], v[194:195], v[210:211]
	v_lshlrev_b32_e32 v188, 16, v172
	v_and_b32_e32 v189, 0xffff0000, v172
	v_lshlrev_b32_e32 v190, 16, v173
	v_and_b32_e32 v191, 0xffff0000, v173
	v_lshlrev_b32_e32 v192, 16, v174
	v_and_b32_e32 v193, 0xffff0000, v174
	v_lshlrev_b32_e32 v194, 16, v175
	v_and_b32_e32 v195, 0xffff0000, v175
	v_pk_fma_f32 v[204:205], v[156:157], v[188:189], v[204:205]
	v_pk_fma_f32 v[206:207], v[158:159], v[190:191], v[206:207]
	v_pk_fma_f32 v[208:209], v[160:161], v[192:193], v[208:209]
	v_pk_fma_f32 v[210:211], v[162:163], v[194:195], v[210:211]
	v_lshlrev_b32_e32 v188, 16, v176
	v_and_b32_e32 v189, 0xffff0000, v176
	v_lshlrev_b32_e32 v190, 16, v177
	v_and_b32_e32 v191, 0xffff0000, v177
	v_lshlrev_b32_e32 v192, 16, v178
	v_and_b32_e32 v193, 0xffff0000, v178
	v_lshlrev_b32_e32 v194, 16, v179
	v_and_b32_e32 v195, 0xffff0000, v179
	v_pk_fma_f32 v[204:205], v[164:165], v[188:189], v[204:205]
	v_pk_fma_f32 v[206:207], v[166:167], v[190:191], v[206:207]
	v_pk_fma_f32 v[208:209], v[168:169], v[192:193], v[208:209]
	v_pk_fma_f32 v[210:211], v[170:171], v[194:195], v[210:211]
	v_mul_f32_e32 v212, 0xbfb8aa3b, v204
	v_mul_f32_e32 v213, 0xbfb8aa3b, v205
	v_mul_f32_e32 v214, 0xbfb8aa3b, v206
	v_mul_f32_e32 v215, 0xbfb8aa3b, v207
	v_mul_f32_e32 v216, 0xbfb8aa3b, v208
	v_mul_f32_e32 v217, 0xbfb8aa3b, v209
	v_mul_f32_e32 v218, 0xbfb8aa3b, v210
	v_mul_f32_e32 v219, 0xbfb8aa3b, v211
	v_mul_f32_e32 v188, 0x3db504f3, v204
	v_mul_f32_e32 v189, 0x3db504f3, v205
	v_mul_f32_e32 v190, 0x3db504f3, v206
	v_mul_f32_e32 v191, 0x3db504f3, v207
	v_mul_f32_e32 v192, 0x3db504f3, v208
	v_mul_f32_e32 v193, 0x3db504f3, v209
	v_mul_f32_e32 v194, 0x3db504f3, v210
	v_mul_f32_e32 v195, 0x3db504f3, v211
	v_exp_f32_e32 v212, v212
	v_exp_f32_e32 v213, v213
	v_exp_f32_e32 v214, v214
	v_exp_f32_e32 v215, v215
	v_exp_f32_e32 v216, v216
	v_exp_f32_e32 v217, v217
	v_exp_f32_e32 v218, v218
	v_exp_f32_e32 v219, v219
	v_add_f32_e32 v212, 1.0, v212
	v_add_f32_e32 v213, 1.0, v213
	v_add_f32_e32 v214, 1.0, v214
	v_add_f32_e32 v215, 1.0, v215
	v_add_f32_e32 v216, 1.0, v216
	v_add_f32_e32 v217, 1.0, v217
	v_add_f32_e32 v218, 1.0, v218
	v_add_f32_e32 v219, 1.0, v219
	v_rcp_f32_e32 v212, v212
	v_rcp_f32_e32 v213, v213
	v_rcp_f32_e32 v214, v214
	v_rcp_f32_e32 v215, v215
	v_rcp_f32_e32 v216, v216
	v_rcp_f32_e32 v217, v217
	v_rcp_f32_e32 v218, v218
	v_rcp_f32_e32 v219, v219
	v_mul_f32_e32 v188, v188, v212
	v_mul_f32_e32 v189, v189, v213
	v_mul_f32_e32 v190, v190, v214
	v_mul_f32_e32 v191, v191, v215
	v_mul_f32_e32 v192, v192, v216
	v_mul_f32_e32 v193, v193, v217
	v_mul_f32_e32 v194, v194, v218
	v_mul_f32_e32 v195, v195, v219
	s_waitcnt lgkmcnt(0)
	v_mul_f32_e32 v188, v196, v188
	v_mul_f32_e32 v189, v196, v189
	v_mul_f32_e32 v190, v196, v190
	v_mul_f32_e32 v191, v196, v191
	v_mul_f32_e32 v192, v196, v192
	v_mul_f32_e32 v193, v196, v193
	v_mul_f32_e32 v194, v196, v194
	v_mul_f32_e32 v195, v196, v195
	v_cvt_pk_bf16_f32 v188, v188, s77
	v_cvt_pk_bf16_f32 v189, v189, s77
	v_cvt_pk_bf16_f32 v190, v190, s77
	v_cvt_pk_bf16_f32 v191, v191, s77
	v_cvt_pk_bf16_f32 v192, v192, s77
	v_cvt_pk_bf16_f32 v193, v193, s77
	v_cvt_pk_bf16_f32 v194, v194, s77
	v_cvt_pk_bf16_f32 v195, v195, s77
	ds_write_b16 v198, v188
	ds_write_b16 v198, v189 offset:144
	ds_write_b16 v198, v190 offset:288
	ds_write_b16 v198, v191 offset:432
	ds_write_b16 v198, v192 offset:576
	ds_write_b16 v198, v193 offset:720
	ds_write_b16 v198, v194 offset:864
	ds_write_b16 v198, v195 offset:1008
